# next-layer prepared weights/biases handed over by write-through stores + counter; ff2 -> in-proj barrier XCD-local for layers 0-2 (each XCD now runs the 4 layers without cross-XCD barriers; only prolo
# speedup vs baseline: 1.0481x; 1.0139x over previous
.LBB0_811:
	s_mov_b32 s6, s71
	s_waitcnt vmcnt(0)
	s_waitcnt lgkmcnt(0)
	s_barrier
	s_and_saveexec_b64 s[0:1], s[26:27]
	s_cbranch_execz .LBB0_848
	v_readlane_b32 s7, v255, 17
	s_waitcnt vmcnt(0) expcnt(0) lgkmcnt(0)
	s_mov_b64 s[4:5], exec
	v_mov_b32_e32 v0, s7
	v_readlane_b32 s7, v255, 18
	ds_read_b32 v2, v0
	v_mbcnt_lo_u32_b32 v1, s4, 0
	v_mov_b32_e32 v0, s7
	ds_read_b32 v0, v0
	v_mbcnt_hi_u32_b32 v1, s5, v1
	s_lshl_b32 s20, s6, 6
	v_cmp_eq_u32_e32 vcc, 0, v1
	s_and_saveexec_b64 s[6:7], vcc
	s_cbranch_execz .LBB0_814
	s_add_i32 s96, s20, 0x500
	s_lshr_b32 s9, s20, 1
	s_add_i32 s9, s9, 0xe50
	v_readlane_b32 s8, v255, 46
	s_cmp_lg_u32 s8, 0
	s_cselect_b32 s96, s9, s96
	s_lshl_b64 s[8:9], s[96:97], 2
	v_readlane_b32 s10, v254, 10
	v_readlane_b32 s11, v254, 11
	s_add_u32 s8, s10, s8
	s_addc_u32 s9, s11, s9
	s_bcnt1_i32_b64 s4, s[4:5]
	v_mov_b32_e32 v3, s4
	global_atomic_add v3, v65, v3, s[8:9] sc0
.LBB0_814:
	s_or_b64 exec, exec, s[6:7]
	s_waitcnt lgkmcnt(1)
	v_cvt_f32_u32_e32 v4, v2
	s_waitcnt vmcnt(0)
	v_readfirstlane_b32 s4, v3
	buffer_inv sc1
	v_sub_u32_e32 v3, 0, v2
	v_rcp_iflag_f32_e32 v4, v4
	v_add_u32_e32 v5, s4, v1
	v_mul_f32_e32 v4, 0x4f7ffffe, v4
	v_cvt_u32_f32_e32 v4, v4
	v_mul_lo_u32 v1, v3, v4
	v_mul_hi_u32 v1, v4, v1
	v_add_u32_e32 v1, v4, v1
	v_mul_hi_u32 v1, v5, v1
	v_mul_lo_u32 v3, v1, v2
	v_sub_u32_e32 v3, v5, v3
	v_add_u32_e32 v4, 1, v1
	v_cmp_ge_u32_e32 vcc, v3, v2
	s_nop 1
	v_cndmask_b32_e32 v1, v1, v4, vcc
	v_sub_u32_e32 v4, v3, v2
	v_cndmask_b32_e32 v3, v3, v4, vcc
	v_add_u32_e32 v4, 1, v1
	v_cmp_ge_u32_e32 vcc, v3, v2
	v_add_u32_e32 v3, 1, v5
	s_nop 0
	v_cndmask_b32_e32 v1, v1, v4, vcc
	v_mul_lo_u32 v4, v2, v1
	v_add_u32_e32 v2, v4, v2
	v_cmp_ne_u32_e32 vcc, v3, v2
	s_and_saveexec_b64 s[4:5], vcc
	s_xor_b64 s[4:5], exec, s[4:5]
	s_cbranch_execz .LBB0_828
	v_readlane_b32 s6, v255, 46
	s_cmp_lg_u32 s6, 0
	s_cbranch_scc0 .Lmy_gpoll_d
	s_lshr_b32 s96, s20, 1
	s_add_i32 s96, s96, 0xe50
	s_lshl_b64 s[6:7], s[96:97], 2
	v_readlane_b32 s8, v254, 10
	v_readlane_b32 s9, v254, 11
	s_add_u32 s8, s8, s6
	s_addc_u32 s9, s9, s7
	s_mov_b32 s21, 0
	s_waitcnt lgkmcnt(0)
	s_nop 1

.LBB0_1838:
	v_readlane_b32 s71, v254, 12
	s_mov_b32 s6, s71
	s_waitcnt vmcnt(0)
	s_barrier
	s_and_saveexec_b64 s[0:1], s[26:27]
	s_cbranch_execz .LBB0_1875
	v_readlane_b32 s7, v255, 17
	s_waitcnt vmcnt(0) expcnt(0) lgkmcnt(0)
	s_mov_b64 s[4:5], exec
	v_mov_b32_e32 v0, s7
	v_readlane_b32 s7, v255, 18
	ds_read_b32 v2, v0
	v_mbcnt_lo_u32_b32 v1, s4, 0
	v_mov_b32_e32 v0, s7
	ds_read_b32 v0, v0
	v_mbcnt_hi_u32_b32 v1, s5, v1
	s_lshl_b32 s20, s6, 6
	v_cmp_eq_u32_e32 vcc, 0, v1
	s_and_saveexec_b64 s[6:7], vcc
	s_cbranch_execz .LBB0_1841
	s_add_i32 s96, s20, 0x500
	s_lshr_b32 s9, s20, 1
	s_add_i32 s9, s9, 0xe50
	v_readlane_b32 s8, v255, 46
	s_cmp_lg_u32 s8, 0
	s_cselect_b32 s96, s9, s96
	s_lshl_b64 s[8:9], s[96:97], 2
	v_readlane_b32 s10, v254, 10
	v_readlane_b32 s11, v254, 11
	s_add_u32 s8, s10, s8
	s_addc_u32 s9, s11, s9
	s_bcnt1_i32_b64 s4, s[4:5]
	v_mov_b32_e32 v3, s4
	global_atomic_add v3, v65, v3, s[8:9] sc0

.LBB0_1990:
	v_ashrrev_i32_e32 v10, 6, v4
	v_ashrrev_i32_e32 v8, 6, v5
	v_lshl_add_u32 v9, v10, 8, v0
	v_lshl_add_u32 v11, v8, 8, v0
	ds_read2st64_b32 v[12:13], v9 offset0:144 offset1:153
	ds_read2st64_b32 v[14:15], v11 offset0:144 offset1:153
	v_add_u32_e32 v7, -2, v7
	v_cmp_eq_u32_e32 vcc, 0, v7
	v_add_u32_e32 v5, 0x400, v5
	s_waitcnt lgkmcnt(1)
	v_mov_b32_e32 v16, v12
	s_waitcnt lgkmcnt(0)
	v_mov_b32_e32 v17, v14
	v_pk_add_f32 v[16:17], v[16:17], 0 op_sel_hi:[1,0]
	v_mov_b32_e32 v14, v13
	v_pk_add_f32 v[12:13], v[16:17], v[14:15]
	ds_read2st64_b32 v[14:15], v9 offset0:162 offset1:171
	ds_read2st64_b32 v[16:17], v11 offset0:162 offset1:171
	v_add_u32_e32 v4, 0x400, v4
	s_or_b64 s[56:57], vcc, s[56:57]
	s_waitcnt lgkmcnt(1)
	v_mov_b32_e32 v18, v14
	s_waitcnt lgkmcnt(0)
	v_mov_b32_e32 v19, v16
	v_pk_add_f32 v[12:13], v[12:13], v[18:19]
	v_mov_b32_e32 v16, v15
	v_pk_add_f32 v[12:13], v[12:13], v[16:17]
	ds_read2st64_b32 v[14:15], v9 offset0:180 offset1:189
	ds_read2st64_b32 v[16:17], v11 offset0:180 offset1:189
	s_waitcnt lgkmcnt(1)
	v_mov_b32_e32 v18, v14
	s_waitcnt lgkmcnt(0)
	v_mov_b32_e32 v19, v16
	v_pk_add_f32 v[12:13], v[12:13], v[18:19]
	v_mov_b32_e32 v16, v15
	v_pk_add_f32 v[12:13], v[12:13], v[16:17]
	ds_read2st64_b32 v[14:15], v9 offset0:198 offset1:207
	ds_read2st64_b32 v[16:17], v11 offset0:198 offset1:207
	v_ashrrev_i32_e32 v11, 31, v10
	v_ashrrev_i32_e32 v9, 31, v8
	v_lshlrev_b64 v[10:11], 14, v[10:11]
	s_waitcnt lgkmcnt(1)
	v_mov_b32_e32 v18, v14
	s_waitcnt lgkmcnt(0)
	v_mov_b32_e32 v19, v16
	v_pk_add_f32 v[12:13], v[12:13], v[18:19]
	v_mov_b32_e32 v16, v15
	v_pk_add_f32 v[12:13], v[12:13], v[16:17]
	v_lshlrev_b64 v[8:9], 14, v[8:9]
	v_pk_add_f32 v[12:13], v[12:13], 0 op_sel_hi:[1,0]
	v_lshl_add_u64 v[10:11], v[2:3], 0, v[10:11]
	v_lshl_add_u64 v[8:9], v[2:3], 0, v[8:9]
	global_store_dword v[10:11], v12, off sc1
	global_store_dword v[8:9], v13, off sc1
	s_andn2_b64 exec, exec, s[56:57]
	s_cbranch_execnz .LBB0_1990
	s_or_b64 exec, exec, s[56:57]
	v_cmp_ne_u32_e32 vcc, v1, v6
	v_lshl_add_u32 v20, v6, 9, v20
	s_orn2_b64 s[56:57], vcc, exec

.LBB0_1994:
	v_ashrrev_i32_e32 v4, 6, v20
	v_lshl_add_u32 v1, v4, 8, v0
	ds_read2st64_b32 v[6:7], v1 offset0:144 offset1:153
	v_cmp_lt_i32_e32 vcc, 63, v20
	s_or_b64 s[34:35], vcc, s[34:35]
	s_waitcnt lgkmcnt(0)
	v_add_f32_e32 v5, 0, v6
	v_add_f32_e32 v5, v5, v7
	ds_read2st64_b32 v[6:7], v1 offset0:162 offset1:171
	s_waitcnt lgkmcnt(0)
	v_add_f32_e32 v5, v5, v6
	v_add_f32_e32 v5, v5, v7
	ds_read2st64_b32 v[6:7], v1 offset0:180 offset1:189
	s_waitcnt lgkmcnt(0)
	v_add_f32_e32 v5, v5, v6
	v_add_f32_e32 v5, v5, v7
	ds_read2st64_b32 v[6:7], v1 offset0:198 offset1:207
	s_waitcnt lgkmcnt(0)
	v_add_f32_e32 v1, v5, v6
	v_ashrrev_i32_e32 v5, 31, v4
	v_add_f32_e32 v1, v1, v7
	v_lshlrev_b64 v[4:5], 14, v[4:5]
	v_add_f32_e32 v1, 0, v1
	v_lshl_add_u64 v[4:5], v[2:3], 0, v[4:5]
	global_store_dword v[4:5], v1, off sc1
	v_add_u32_e32 v1, 0x200, v20
	v_mov_b32_e32 v20, v1
	s_andn2_b64 exec, exec, s[34:35]
	s_cbranch_execnz .LBB0_1994

.LBB0_2074:
	v_ashrrev_i32_e32 v17, 6, v4
	v_ashrrev_i32_e32 v16, 6, v5
	v_lshl_add_u32 v18, v17, 8, v0
	v_lshl_add_u32 v19, v16, 8, v0
	ds_read2st64_b32 v[8:9], v18 offset0:144 offset1:153
	ds_read2st64_b32 v[10:11], v19 offset0:144 offset1:153
	v_add_u32_e32 v7, -2, v7
	v_cmp_eq_u32_e32 vcc, 0, v7
	v_add_u32_e32 v5, 0x400, v5
	s_waitcnt lgkmcnt(1)
	v_mov_b32_e32 v12, v8
	s_waitcnt lgkmcnt(0)
	v_mov_b32_e32 v13, v10
	v_pk_add_f32 v[12:13], v[12:13], 0 op_sel_hi:[1,0]
	v_mov_b32_e32 v10, v9
	v_pk_add_f32 v[8:9], v[12:13], v[10:11]
	ds_read2st64_b32 v[10:11], v18 offset0:162 offset1:171
	ds_read2st64_b32 v[12:13], v19 offset0:162 offset1:171
	v_add_u32_e32 v4, 0x400, v4
	s_or_b64 s[56:57], vcc, s[56:57]
	s_waitcnt lgkmcnt(1)
	v_mov_b32_e32 v14, v10
	s_waitcnt lgkmcnt(0)
	v_mov_b32_e32 v15, v12
	v_pk_add_f32 v[8:9], v[8:9], v[14:15]
	v_mov_b32_e32 v12, v11
	v_pk_add_f32 v[8:9], v[8:9], v[12:13]
	ds_read2st64_b32 v[10:11], v18 offset0:180 offset1:189
	ds_read2st64_b32 v[12:13], v19 offset0:180 offset1:189
	s_waitcnt lgkmcnt(1)
	v_mov_b32_e32 v14, v10
	s_waitcnt lgkmcnt(0)
	v_mov_b32_e32 v15, v12
	v_pk_add_f32 v[8:9], v[8:9], v[14:15]
	v_mov_b32_e32 v12, v11
	v_pk_add_f32 v[8:9], v[8:9], v[12:13]
	ds_read2st64_b32 v[10:11], v18 offset0:198 offset1:207
	ds_read2st64_b32 v[12:13], v19 offset0:198 offset1:207
	s_waitcnt lgkmcnt(1)
	v_mov_b32_e32 v14, v10
	s_waitcnt lgkmcnt(0)
	v_mov_b32_e32 v15, v12
	v_pk_add_f32 v[8:9], v[8:9], v[14:15]
	v_mov_b32_e32 v12, v11
	v_pk_add_f32 v[8:9], v[8:9], v[12:13]
	v_mad_i64_i32 v[10:11], s[0:1], v17, s78, v[2:3]
	v_pk_add_f32 v[8:9], v[8:9], 0 op_sel_hi:[1,0]
	v_mad_i64_i32 v[12:13], s[0:1], v16, s78, v[2:3]
	global_store_dword v[10:11], v8, off sc1
	global_store_dword v[12:13], v9, off sc1
	s_andn2_b64 exec, exec, s[56:57]
	s_cbranch_execnz .LBB0_2074
	s_or_b64 exec, exec, s[56:57]
	v_cmp_ne_u32_e32 vcc, v1, v6
	v_lshl_add_u32 v20, v6, 9, v20
	s_orn2_b64 s[56:57], vcc, exec

.LBB0_2078:
	v_ashrrev_i32_e32 v1, 6, v20
	v_lshl_add_u32 v6, v1, 8, v0
	ds_read2st64_b32 v[4:5], v6 offset0:144 offset1:153
	v_cmp_lt_i32_e32 vcc, 63, v20
	s_or_b64 s[6:7], vcc, s[6:7]
	s_waitcnt lgkmcnt(0)
	v_add_f32_e32 v4, 0, v4
	v_add_f32_e32 v7, v4, v5
	ds_read2st64_b32 v[4:5], v6 offset0:162 offset1:171
	s_waitcnt lgkmcnt(0)
	v_add_f32_e32 v4, v7, v4
	v_add_f32_e32 v7, v4, v5
	ds_read2st64_b32 v[4:5], v6 offset0:180 offset1:189
	s_waitcnt lgkmcnt(0)
	v_add_f32_e32 v4, v7, v4
	v_add_f32_e32 v7, v4, v5
	ds_read2st64_b32 v[4:5], v6 offset0:198 offset1:207
	s_waitcnt lgkmcnt(0)
	v_add_f32_e32 v4, v7, v4
	v_add_f32_e32 v4, v4, v5
	v_add_f32_e32 v6, 0, v4
	v_mad_i64_i32 v[4:5], s[0:1], v1, s78, v[2:3]
	v_add_u32_e32 v1, 0x200, v20
	v_mov_b32_e32 v20, v1
	global_store_dword v[4:5], v6, off sc1
	s_andn2_b64 exec, exec, s[6:7]
	s_cbranch_execnz .LBB0_2078
	s_branch .LBB0_1910
.LBB0_2079:
	s_mov_b32 s4, s71
	s_waitcnt vmcnt(0)
	s_waitcnt lgkmcnt(0)
	s_barrier
	s_and_saveexec_b64 s[6:7], s[26:27]
	s_cbranch_execz .LBB0_2116
	s_cmp_lt_u32 s74, 3
	s_cbranch_scc0 .Lmy_a_nopub
	s_cmpk_lt_i32 s2, 0xc0
	s_cbranch_scc1 .Lmy_a_nopub
	v_readlane_b32 s0, v254, 10
	v_readlane_b32 s1, v254, 11
	v_mov_b32_e32 v0, 0x3880
	v_mov_b32_e32 v1, 1
	s_nop 3
	global_atomic_add v0, v1, s[0:1]
.Lmy_a_nopub:
	v_readlane_b32 s0, v255, 17
	s_waitcnt vmcnt(0) expcnt(0) lgkmcnt(0)
	s_mov_b64 s[16:17], exec
	v_mov_b32_e32 v0, s0
	v_readlane_b32 s0, v255, 18
	ds_read_b32 v2, v0
	v_mbcnt_lo_u32_b32 v1, s16, 0
	v_mov_b32_e32 v0, s0
	ds_read_b32 v0, v0
	v_mbcnt_hi_u32_b32 v1, s17, v1
	s_lshl_b32 s4, s4, 6
	v_cmp_eq_u32_e32 vcc, 0, v1
	s_and_saveexec_b64 s[18:19], vcc
	s_cbranch_execz .LBB0_2082
	s_add_i32 s96, s4, 0x500
	s_lshr_b32 s1, s4, 1
	s_add_i32 s1, s1, 0xe50
	v_readlane_b32 s0, v255, 46
	s_cmp_lg_u32 s0, 0
	s_cselect_b32 s96, s1, s96
	s_lshl_b64 s[0:1], s[96:97], 2
	v_readlane_b32 s8, v254, 10
	v_readlane_b32 s9, v254, 11
	s_add_u32 s0, s8, s0
	s_addc_u32 s1, s9, s1
	s_bcnt1_i32_b64 s5, s[16:17]
	v_mov_b32_e32 v3, s5
	global_atomic_add v3, v65, v3, s[0:1] sc0
.LBB0_2082:
	s_or_b64 exec, exec, s[18:19]
	s_waitcnt lgkmcnt(1)
	v_cvt_f32_u32_e32 v4, v2
	s_waitcnt vmcnt(0)
	v_readfirstlane_b32 s0, v3
	buffer_inv sc1
	v_sub_u32_e32 v3, 0, v2
	v_rcp_iflag_f32_e32 v4, v4
	v_add_u32_e32 v5, s0, v1
	v_mul_f32_e32 v4, 0x4f7ffffe, v4
	v_cvt_u32_f32_e32 v4, v4
	v_mul_lo_u32 v1, v3, v4
	v_mul_hi_u32 v1, v4, v1
	v_add_u32_e32 v1, v4, v1
	v_mul_hi_u32 v1, v5, v1
	v_mul_lo_u32 v3, v1, v2
	v_sub_u32_e32 v3, v5, v3
	v_add_u32_e32 v4, 1, v1
	v_cmp_ge_u32_e32 vcc, v3, v2
	s_nop 1
	v_cndmask_b32_e32 v1, v1, v4, vcc
	v_sub_u32_e32 v4, v3, v2
	v_cndmask_b32_e32 v3, v3, v4, vcc
	v_add_u32_e32 v4, 1, v1
	v_cmp_ge_u32_e32 vcc, v3, v2
	v_add_u32_e32 v3, 1, v5
	s_nop 0
	v_cndmask_b32_e32 v1, v1, v4, vcc
	v_mul_lo_u32 v4, v2, v1
	v_add_u32_e32 v2, v4, v2
	v_cmp_ne_u32_e32 vcc, v3, v2
	s_and_saveexec_b64 s[0:1], vcc
	s_xor_b64 s[16:17], exec, s[0:1]
	s_cbranch_execz .LBB0_2096
	v_readlane_b32 s0, v255, 46
	s_cmp_lg_u32 s0, 0
	s_cbranch_scc0 .Lmy_gpoll_a
	s_lshr_b32 s96, s4, 1
	s_add_i32 s96, s96, 0xe50
	s_lshl_b64 s[0:1], s[96:97], 2
	v_readlane_b32 s8, v254, 10
	v_readlane_b32 s9, v254, 11
	s_add_u32 s20, s8, s0
	s_addc_u32 s21, s9, s1
	s_mov_b32 s5, 0
	s_waitcnt lgkmcnt(0)
	s_nop 1

.LBB0_2132:
	s_mov_b32 s4, s71
	s_waitcnt vmcnt(0)
	s_waitcnt lgkmcnt(0)
	s_barrier
	s_and_saveexec_b64 s[6:7], s[26:27]
	v_readlane_b32 s33, v255, 29
	s_cbranch_execz .LBB0_2169
	v_readlane_b32 s0, v255, 17
	s_waitcnt vmcnt(0) expcnt(0) lgkmcnt(0)
	s_mov_b64 s[18:19], exec
	v_mov_b32_e32 v0, s0
	v_readlane_b32 s0, v255, 18
	ds_read_b32 v2, v0
	v_mbcnt_lo_u32_b32 v1, s18, 0
	v_mov_b32_e32 v0, s0
	ds_read_b32 v0, v0
	v_mbcnt_hi_u32_b32 v1, s19, v1
	s_lshl_b32 s4, s4, 6
	v_cmp_eq_u32_e32 vcc, 0, v1
	s_and_saveexec_b64 s[20:21], vcc
	s_cbranch_execz .LBB0_2135
	s_add_i32 s96, s4, 0x500
	s_lshr_b32 s1, s4, 1
	s_add_i32 s1, s1, 0xe50
	v_readlane_b32 s0, v255, 46
	s_cmp_lg_u32 s0, 0
	s_cselect_b32 s96, s1, s96
	s_lshl_b64 s[0:1], s[96:97], 2
	v_readlane_b32 s8, v254, 10
	v_readlane_b32 s9, v254, 11
	s_add_u32 s0, s8, s0
	s_addc_u32 s1, s9, s1
	s_bcnt1_i32_b64 s5, s[18:19]
	v_mov_b32_e32 v3, s5
	global_atomic_add v3, v65, v3, s[0:1] sc0
.LBB0_2135:
	s_or_b64 exec, exec, s[20:21]
	s_waitcnt lgkmcnt(1)
	v_cvt_f32_u32_e32 v4, v2
	s_waitcnt vmcnt(0)
	v_readfirstlane_b32 s0, v3
	buffer_inv sc1
	v_sub_u32_e32 v3, 0, v2
	v_rcp_iflag_f32_e32 v4, v4
	v_add_u32_e32 v5, s0, v1
	v_mul_f32_e32 v4, 0x4f7ffffe, v4
	v_cvt_u32_f32_e32 v4, v4
	v_mul_lo_u32 v1, v3, v4
	v_mul_hi_u32 v1, v4, v1
	v_add_u32_e32 v1, v4, v1
	v_mul_hi_u32 v1, v5, v1
	v_mul_lo_u32 v3, v1, v2
	v_sub_u32_e32 v3, v5, v3
	v_add_u32_e32 v4, 1, v1
	v_cmp_ge_u32_e32 vcc, v3, v2
	s_nop 1
	v_cndmask_b32_e32 v1, v1, v4, vcc
	v_sub_u32_e32 v4, v3, v2
	v_cndmask_b32_e32 v3, v3, v4, vcc
	v_add_u32_e32 v4, 1, v1
	v_cmp_ge_u32_e32 vcc, v3, v2
	v_add_u32_e32 v3, 1, v5
	s_nop 0
	v_cndmask_b32_e32 v1, v1, v4, vcc
	v_mul_lo_u32 v4, v2, v1
	v_add_u32_e32 v2, v4, v2
	v_cmp_ne_u32_e32 vcc, v3, v2
	s_and_saveexec_b64 s[0:1], vcc
	s_xor_b64 s[18:19], exec, s[0:1]
	s_cbranch_execz .LBB0_2149
	v_readlane_b32 s0, v255, 46
	s_cmp_lg_u32 s0, 0
	s_cbranch_scc0 .Lmy_gpoll_b
	s_lshr_b32 s96, s4, 1
	s_add_i32 s96, s96, 0xe50
	s_lshl_b64 s[0:1], s[96:97], 2
	v_readlane_b32 s8, v254, 10
	v_readlane_b32 s9, v254, 11
	s_add_u32 s22, s8, s0
	s_addc_u32 s23, s9, s1
	s_mov_b32 s5, 0
	s_waitcnt lgkmcnt(0)
	s_nop 1

.LBB0_2244:
	s_or_b64 exec, exec, s[4:5]
	v_ashrrev_i32_e32 v25, 31, v24
	s_waitcnt lgkmcnt(3)
	v_cvt_pk_bf16_f32 v16, v16, v17
	s_waitcnt lgkmcnt(2)
	v_cvt_pk_bf16_f32 v17, v18, v19
	s_waitcnt lgkmcnt(1)
	v_cvt_pk_bf16_f32 v18, v20, v21
	v_lshlrev_b64 v[20:21], 11, v[24:25]
	s_waitcnt lgkmcnt(0)
	v_cvt_pk_bf16_f32 v19, v22, v23
	v_lshl_add_u64 v[14:15], v[14:15], 0, v[20:21]
	global_store_dwordx4 v[14:15], v[16:19], off sc1
	s_waitcnt lgkmcnt(0)

.LBB0_2246:
	s_movk_i32 s4, 0x57f
	v_cmp_lt_i32_e32 vcc, s4, v0
	s_and_saveexec_b64 s[4:5], vcc
	s_xor_b64 s[4:5], exec, s[4:5]
	s_cbranch_execz .LBB0_2256
	s_movk_i32 s6, 0x77f
	v_cmp_lt_u32_e32 vcc, s6, v0
	v_add_u32_e32 v14, 0x600, v12
	s_and_saveexec_b64 s[6:7], vcc
	s_xor_b64 s[6:7], exec, s[6:7]
	s_cbranch_execz .LBB0_2253
	s_movk_i32 s16, 0xf7f
	v_cmp_lt_u32_e32 vcc, s16, v0
	s_and_saveexec_b64 s[16:17], vcc
	s_xor_b64 s[16:17], exec, s[16:17]
	s_cbranch_execz .LBB0_2250
	v_and_b32_e32 v17, 0x1ffc0, v38
	v_and_b32_e32 v16, 0x3e0, v14
	v_or_b32_e32 v14, v17, v1
	v_lshlrev_b32_e32 v14, 10, v14
	v_or3_b32 v14, v14, v13, v16
	v_lshlrev_b32_e32 v64, 2, v14
	v_lshl_add_u64 v[14:15], s[8:9], 0, v[64:65]
	v_add_co_u32_e32 v18, vcc, 0x2000, v14
	s_mov_b32 s18, 0x10000
	s_nop 0
	v_addc_co_u32_e32 v19, vcc, 0, v15, vcc
	global_load_dword v21, v[18:19], off
	v_add_co_u32_e32 v18, vcc, 0x4000, v14
	global_load_dword v20, v64, s[8:9]
	s_nop 0
	v_addc_co_u32_e32 v19, vcc, 0, v15, vcc
	global_load_dword v22, v[18:19], off
	v_add_co_u32_e32 v18, vcc, 0x6000, v14
	s_nop 1
	v_addc_co_u32_e32 v19, vcc, 0, v15, vcc
	global_load_dword v23, v[18:19], off
	v_add_co_u32_e32 v18, vcc, 0x8000, v14
	s_nop 1
	v_addc_co_u32_e32 v19, vcc, 0, v15, vcc
	global_load_dword v24, v[18:19], off
	v_add_co_u32_e32 v18, vcc, 0xa000, v14
	s_nop 1
	v_addc_co_u32_e32 v19, vcc, 0, v15, vcc
	global_load_dword v25, v[18:19], off
	v_add_co_u32_e32 v18, vcc, 0xc000, v14
	s_nop 1
	v_addc_co_u32_e32 v19, vcc, 0, v15, vcc
	global_load_dword v26, v[18:19], off
	v_add_co_u32_e32 v18, vcc, 0xe000, v14
	s_nop 1
	v_addc_co_u32_e32 v19, vcc, 0, v15, vcc
	global_load_dword v27, v[18:19], off
	v_add_co_u32_e32 v18, vcc, s18, v14
	s_mov_b32 s18, 0x12000
	s_nop 0
	v_addc_co_u32_e32 v19, vcc, 0, v15, vcc
	global_load_dword v39, v[18:19], off
	v_add_co_u32_e32 v18, vcc, s18, v14
	s_mov_b32 s18, 0x14000
	s_nop 0
	v_addc_co_u32_e32 v19, vcc, 0, v15, vcc
	global_load_dword v40, v[18:19], off
	v_add_co_u32_e32 v18, vcc, s18, v14
	s_mov_b32 s18, 0x16000
	s_nop 0
	v_addc_co_u32_e32 v19, vcc, 0, v15, vcc
	global_load_dword v41, v[18:19], off
	v_add_co_u32_e32 v18, vcc, s18, v14
	s_mov_b32 s18, 0x18000
	s_nop 0
	v_addc_co_u32_e32 v19, vcc, 0, v15, vcc
	global_load_dword v42, v[18:19], off
	v_add_co_u32_e32 v18, vcc, s18, v14
	s_mov_b32 s18, 0x1a000
	s_nop 0
	v_addc_co_u32_e32 v19, vcc, 0, v15, vcc
	global_load_dword v43, v[18:19], off
	v_add_co_u32_e32 v18, vcc, s18, v14
	s_mov_b32 s18, 0x1c000
	s_nop 0
	v_addc_co_u32_e32 v19, vcc, 0, v15, vcc
	global_load_dword v44, v[18:19], off
	v_add_co_u32_e32 v18, vcc, s18, v14
	s_mov_b32 s18, 0x1e000
	s_nop 0
	v_addc_co_u32_e32 v19, vcc, 0, v15, vcc
	global_load_dword v45, v[18:19], off
	v_add_co_u32_e32 v18, vcc, s18, v14
	s_mov_b32 s18, 0x20000
	s_nop 0
	v_addc_co_u32_e32 v19, vcc, 0, v15, vcc
	global_load_dword v46, v[18:19], off
	v_add_co_u32_e32 v18, vcc, s18, v14
	s_mov_b32 s18, 0x22000
	s_nop 0
	v_addc_co_u32_e32 v19, vcc, 0, v15, vcc
	global_load_dword v47, v[18:19], off
	v_add_co_u32_e32 v18, vcc, s18, v14
	s_mov_b32 s18, 0x24000
	s_nop 0
	v_addc_co_u32_e32 v19, vcc, 0, v15, vcc
	global_load_dword v48, v[18:19], off
	v_add_co_u32_e32 v18, vcc, s18, v14
	s_mov_b32 s18, 0x26000
	s_nop 0
	v_addc_co_u32_e32 v19, vcc, 0, v15, vcc
	global_load_dword v49, v[18:19], off
	v_add_co_u32_e32 v18, vcc, s18, v14
	s_mov_b32 s18, 0x28000
	s_nop 0
	v_addc_co_u32_e32 v19, vcc, 0, v15, vcc
	global_load_dword v50, v[18:19], off
	v_add_co_u32_e32 v18, vcc, s18, v14
	s_mov_b32 s18, 0x2a000
	s_nop 0
	v_addc_co_u32_e32 v19, vcc, 0, v15, vcc
	global_load_dword v51, v[18:19], off
	v_add_co_u32_e32 v18, vcc, s18, v14
	s_mov_b32 s18, 0x2c000
	s_nop 0
	v_addc_co_u32_e32 v19, vcc, 0, v15, vcc
	global_load_dword v52, v[18:19], off
	v_add_co_u32_e32 v18, vcc, s18, v14
	s_mov_b32 s18, 0x2e000
	s_nop 0
	v_addc_co_u32_e32 v19, vcc, 0, v15, vcc
	global_load_dword v53, v[18:19], off
	v_add_co_u32_e32 v18, vcc, s18, v14
	s_mov_b32 s18, 0x30000
	s_nop 0
	v_addc_co_u32_e32 v19, vcc, 0, v15, vcc
	global_load_dword v54, v[18:19], off
	v_add_co_u32_e32 v18, vcc, s18, v14
	s_mov_b32 s18, 0x32000
	s_nop 0
	v_addc_co_u32_e32 v19, vcc, 0, v15, vcc
	global_load_dword v55, v[18:19], off
	v_add_co_u32_e32 v18, vcc, s18, v14
	s_mov_b32 s18, 0x34000
	s_nop 0
	v_addc_co_u32_e32 v19, vcc, 0, v15, vcc
	global_load_dword v56, v[18:19], off
	v_add_co_u32_e32 v18, vcc, s18, v14
	s_mov_b32 s18, 0x36000
	s_nop 0
	v_addc_co_u32_e32 v19, vcc, 0, v15, vcc
	global_load_dword v57, v[18:19], off
	v_add_co_u32_e32 v18, vcc, s18, v14
	s_mov_b32 s18, 0x38000
	s_nop 0
	v_addc_co_u32_e32 v19, vcc, 0, v15, vcc
	global_load_dword v58, v[18:19], off
	v_add_co_u32_e32 v18, vcc, s18, v14
	s_mov_b32 s18, 0x3a000
	s_nop 0
	v_addc_co_u32_e32 v19, vcc, 0, v15, vcc
	global_load_dword v59, v[18:19], off
	v_add_co_u32_e32 v18, vcc, s18, v14
	s_mov_b32 s18, 0x3c000
	s_nop 0
	v_addc_co_u32_e32 v19, vcc, 0, v15, vcc
	global_load_dword v60, v[18:19], off
	v_add_co_u32_e32 v18, vcc, s18, v14
	s_mov_b32 s18, 0x3e000
	s_nop 0
	v_addc_co_u32_e32 v19, vcc, 0, v15, vcc
	v_add_co_u32_e32 v14, vcc, s18, v14
	global_load_dword v18, v[18:19], off
	s_nop 0
	v_addc_co_u32_e32 v15, vcc, 0, v15, vcc
	global_load_dword v14, v[14:15], off
	v_add_u32_e32 v15, 0x400, v28
	s_waitcnt vmcnt(0)
	ds_write2_b32 v28, v20, v21 offset1:66
	ds_write2_b32 v28, v22, v23 offset0:132 offset1:198
	ds_write2_b32 v15, v24, v25 offset0:8 offset1:74
	ds_write2_b32 v15, v26, v27 offset0:140 offset1:206
	v_add_u32_e32 v15, 0x800, v28
	ds_write2_b32 v15, v39, v40 offset0:16 offset1:82
	ds_write2_b32 v15, v41, v42 offset0:148 offset1:214
	v_add_u32_e32 v15, 0xc00, v28
	ds_write2_b32 v15, v43, v44 offset0:24 offset1:90
	ds_write2_b32 v15, v45, v46 offset0:156 offset1:222
	v_add_u32_e32 v15, 0x1000, v28
	ds_write2_b32 v15, v47, v48 offset0:32 offset1:98
	ds_write2_b32 v15, v49, v50 offset0:164 offset1:230
	v_add_u32_e32 v15, 0x1400, v28
	ds_write2_b32 v15, v51, v52 offset0:40 offset1:106
	ds_write2_b32 v15, v53, v54 offset0:172 offset1:238
	v_add_u32_e32 v15, 0x1800, v28
	ds_write2_b32 v15, v55, v56 offset0:48 offset1:114
	ds_write2_b32 v15, v57, v58 offset0:180 offset1:246
	v_add_u32_e32 v15, 0x1c00, v28
	ds_write2_b32 v15, v59, v60 offset0:56 offset1:122
	ds_write2_b32 v15, v18, v14 offset0:188 offset1:254
	s_waitcnt lgkmcnt(0)
	ds_read2_b32 v[22:23], v30 offset0:33 offset1:41
	ds_read2_b32 v[24:25], v30 offset1:8
	ds_read2_b32 v[26:27], v30 offset0:66 offset1:74
	ds_read2_b32 v[40:41], v30 offset0:99 offset1:107
	ds_read2_b32 v[42:43], v30 offset0:132 offset1:140
	ds_read2_b32 v[44:45], v30 offset0:165 offset1:173
	ds_read2_b32 v[46:47], v30 offset0:198 offset1:206
	ds_read2_b32 v[48:49], v30 offset0:231 offset1:239
	v_lshlrev_b32_e32 v64, 1, v17
	v_or_b32_e32 v17, v16, v29
	v_lshl_add_u64 v[14:15], v[2:3], 0, v[64:65]
	v_lshlrev_b32_e32 v64, 13, v17
	v_or_b32_e32 v17, v16, v31
	s_waitcnt lgkmcnt(0)
	v_cvt_pk_bf16_f32 v18, v24, v22
	v_cvt_pk_bf16_f32 v19, v26, v40
	v_cvt_pk_bf16_f32 v20, v42, v44
	v_cvt_pk_bf16_f32 v21, v46, v48
	v_lshl_add_u64 v[50:51], v[14:15], 0, v[64:65]
	v_lshlrev_b32_e32 v64, 13, v17
	global_store_dwordx4 v[50:51], v[18:21], off sc1
	v_or_b32_e32 v17, v16, v32
	v_or_b32_e32 v16, v16, v33
	v_cvt_pk_bf16_f32 v18, v25, v23
	v_cvt_pk_bf16_f32 v19, v27, v41
	v_cvt_pk_bf16_f32 v20, v43, v45
	v_cvt_pk_bf16_f32 v21, v47, v49
	v_lshl_add_u64 v[22:23], v[14:15], 0, v[64:65]
	global_store_dwordx4 v[22:23], v[18:21], off sc1
	ds_read2_b32 v[22:23], v30 offset0:49 offset1:57
	ds_read2_b32 v[24:25], v30 offset0:16 offset1:24
	ds_read2_b32 v[26:27], v30 offset0:82 offset1:90
	ds_read2_b32 v[40:41], v30 offset0:115 offset1:123
	ds_read2_b32 v[42:43], v30 offset0:148 offset1:156
	ds_read2_b32 v[44:45], v30 offset0:181 offset1:189
	ds_read2_b32 v[46:47], v30 offset0:214 offset1:222
	ds_read2_b32 v[48:49], v30 offset0:247 offset1:255
	v_lshlrev_b32_e32 v64, 13, v17
	s_waitcnt lgkmcnt(6)
	v_cvt_pk_bf16_f32 v18, v24, v22
	s_waitcnt lgkmcnt(4)
	v_cvt_pk_bf16_f32 v19, v26, v40
	s_waitcnt lgkmcnt(2)
	v_cvt_pk_bf16_f32 v20, v42, v44
	s_waitcnt lgkmcnt(0)
	v_cvt_pk_bf16_f32 v21, v46, v48
	v_lshl_add_u64 v[50:51], v[14:15], 0, v[64:65]
	v_lshlrev_b32_e32 v64, 13, v16
	global_store_dwordx4 v[50:51], v[18:21], off sc1
	v_lshl_add_u64 v[14:15], v[14:15], 0, v[64:65]
	s_nop 0
	v_cvt_pk_bf16_f32 v18, v25, v23
	v_cvt_pk_bf16_f32 v19, v27, v41
	v_cvt_pk_bf16_f32 v20, v43, v45
	v_cvt_pk_bf16_f32 v21, v47, v49
	global_store_dwordx4 v[14:15], v[18:21], off sc1
	s_waitcnt lgkmcnt(0)
.LBB0_2250:
	s_andn2_saveexec_b64 s[16:17], s[16:17]
	s_cbranch_execz .LBB0_2252
	v_add_u32_e32 v15, 0xf880, v0
	v_lshrrev_b32_e32 v15, 1, v15
	v_and_b32_e32 v17, 0x7fc0, v15
	v_and_b32_e32 v16, 0xfe0, v14
	v_or_b32_e32 v14, v17, v1
	v_lshlrev_b32_e32 v14, 12, v14
	v_or3_b32 v14, v14, v13, v16
	v_lshlrev_b32_e32 v64, 2, v14
	v_lshl_add_u64 v[14:15], s[10:11], 0, v[64:65]
	v_add_co_u32_e32 v18, vcc, 0x8000, v14
	s_mov_b32 s18, 0x10000
	s_nop 0
	v_addc_co_u32_e32 v19, vcc, 0, v15, vcc
	global_load_dword v21, v[18:19], off
	v_add_co_u32_e32 v18, vcc, s18, v14
	s_mov_b32 s18, 0x18000
	s_nop 0
	v_addc_co_u32_e32 v19, vcc, 0, v15, vcc
	global_load_dword v22, v[18:19], off
	v_add_co_u32_e32 v18, vcc, s18, v14
	global_load_dword v20, v64, s[10:11]
	s_nop 0
	v_addc_co_u32_e32 v19, vcc, 0, v15, vcc
	global_load_dword v23, v[18:19], off
	v_add_co_u32_e32 v18, vcc, 0x20000, v14
	s_nop 1
	v_addc_co_u32_e32 v19, vcc, 0, v15, vcc
	global_load_dword v24, v[18:19], off
	v_add_co_u32_e32 v18, vcc, 0x28000, v14
	s_nop 1
	v_addc_co_u32_e32 v19, vcc, 0, v15, vcc
	global_load_dword v25, v[18:19], off
	v_add_co_u32_e32 v18, vcc, 0x30000, v14
	s_nop 1
	v_addc_co_u32_e32 v19, vcc, 0, v15, vcc
	global_load_dword v26, v[18:19], off
	v_add_co_u32_e32 v18, vcc, 0x38000, v14
	s_nop 1
	v_addc_co_u32_e32 v19, vcc, 0, v15, vcc
	global_load_dword v27, v[18:19], off
	v_add_co_u32_e32 v18, vcc, 0x40000, v14
	s_nop 1
	v_addc_co_u32_e32 v19, vcc, 0, v15, vcc
	global_load_dword v39, v[18:19], off
	v_add_co_u32_e32 v18, vcc, 0x48000, v14
	s_nop 1
	v_addc_co_u32_e32 v19, vcc, 0, v15, vcc
	global_load_dword v40, v[18:19], off
	v_add_co_u32_e32 v18, vcc, 0x50000, v14
	s_nop 1
	v_addc_co_u32_e32 v19, vcc, 0, v15, vcc
	global_load_dword v41, v[18:19], off
	v_add_co_u32_e32 v18, vcc, 0x58000, v14
	s_nop 1
	v_addc_co_u32_e32 v19, vcc, 0, v15, vcc
	global_load_dword v42, v[18:19], off
	v_add_co_u32_e32 v18, vcc, 0x60000, v14
	s_nop 1
	v_addc_co_u32_e32 v19, vcc, 0, v15, vcc
	global_load_dword v43, v[18:19], off
	v_add_co_u32_e32 v18, vcc, 0x68000, v14
	s_nop 1
	v_addc_co_u32_e32 v19, vcc, 0, v15, vcc
	global_load_dword v44, v[18:19], off
	v_add_co_u32_e32 v18, vcc, 0x70000, v14
	s_nop 1
	v_addc_co_u32_e32 v19, vcc, 0, v15, vcc
	global_load_dword v45, v[18:19], off
	v_add_co_u32_e32 v18, vcc, 0x78000, v14
	s_nop 1
	v_addc_co_u32_e32 v19, vcc, 0, v15, vcc
	global_load_dword v46, v[18:19], off
	v_add_co_u32_e32 v18, vcc, 0x80000, v14
	s_nop 1
	v_addc_co_u32_e32 v19, vcc, 0, v15, vcc
	global_load_dword v47, v[18:19], off
	v_add_co_u32_e32 v18, vcc, 0x88000, v14
	s_nop 1
	v_addc_co_u32_e32 v19, vcc, 0, v15, vcc
	global_load_dword v48, v[18:19], off
	v_add_co_u32_e32 v18, vcc, 0x90000, v14
	s_nop 1
	v_addc_co_u32_e32 v19, vcc, 0, v15, vcc
	global_load_dword v49, v[18:19], off
	v_add_co_u32_e32 v18, vcc, 0x98000, v14
	s_nop 1
	v_addc_co_u32_e32 v19, vcc, 0, v15, vcc
	global_load_dword v50, v[18:19], off
	v_add_co_u32_e32 v18, vcc, 0xa0000, v14
	s_nop 1
	v_addc_co_u32_e32 v19, vcc, 0, v15, vcc
	global_load_dword v51, v[18:19], off
	v_add_co_u32_e32 v18, vcc, 0xa8000, v14
	s_nop 1
	v_addc_co_u32_e32 v19, vcc, 0, v15, vcc
	global_load_dword v52, v[18:19], off
	v_add_co_u32_e32 v18, vcc, 0xb0000, v14
	s_nop 1
	v_addc_co_u32_e32 v19, vcc, 0, v15, vcc
	global_load_dword v53, v[18:19], off
	v_add_co_u32_e32 v18, vcc, 0xb8000, v14
	s_nop 1
	v_addc_co_u32_e32 v19, vcc, 0, v15, vcc
	global_load_dword v54, v[18:19], off
	v_add_co_u32_e32 v18, vcc, 0xc0000, v14
	s_nop 1
	v_addc_co_u32_e32 v19, vcc, 0, v15, vcc
	global_load_dword v55, v[18:19], off
	v_add_co_u32_e32 v18, vcc, 0xc8000, v14
	s_nop 1
	v_addc_co_u32_e32 v19, vcc, 0, v15, vcc
	global_load_dword v56, v[18:19], off
	v_add_co_u32_e32 v18, vcc, 0xd0000, v14
	s_nop 1
	v_addc_co_u32_e32 v19, vcc, 0, v15, vcc
	global_load_dword v57, v[18:19], off
	v_add_co_u32_e32 v18, vcc, 0xd8000, v14
	s_nop 1
	v_addc_co_u32_e32 v19, vcc, 0, v15, vcc
	global_load_dword v58, v[18:19], off
	v_add_co_u32_e32 v18, vcc, 0xe0000, v14
	s_nop 1
	v_addc_co_u32_e32 v19, vcc, 0, v15, vcc
	global_load_dword v59, v[18:19], off
	v_add_co_u32_e32 v18, vcc, 0xe8000, v14
	s_nop 1
	v_addc_co_u32_e32 v19, vcc, 0, v15, vcc
	global_load_dword v60, v[18:19], off
	v_add_co_u32_e32 v18, vcc, 0xf0000, v14
	s_nop 1
	v_addc_co_u32_e32 v19, vcc, 0, v15, vcc
	v_add_co_u32_e32 v14, vcc, 0xf8000, v14
	global_load_dword v18, v[18:19], off
	s_nop 0
	v_addc_co_u32_e32 v15, vcc, 0, v15, vcc
	global_load_dword v14, v[14:15], off
	v_add_u32_e32 v15, 0x400, v28
	s_waitcnt vmcnt(0)
	ds_write2_b32 v28, v20, v21 offset1:66
	ds_write2_b32 v28, v22, v23 offset0:132 offset1:198
	ds_write2_b32 v15, v24, v25 offset0:8 offset1:74
	ds_write2_b32 v15, v26, v27 offset0:140 offset1:206
	v_add_u32_e32 v15, 0x800, v28
	ds_write2_b32 v15, v39, v40 offset0:16 offset1:82
	ds_write2_b32 v15, v41, v42 offset0:148 offset1:214
	v_add_u32_e32 v15, 0xc00, v28
	ds_write2_b32 v15, v43, v44 offset0:24 offset1:90
	ds_write2_b32 v15, v45, v46 offset0:156 offset1:222
	v_add_u32_e32 v15, 0x1000, v28
	ds_write2_b32 v15, v47, v48 offset0:32 offset1:98
	ds_write2_b32 v15, v49, v50 offset0:164 offset1:230
	v_add_u32_e32 v15, 0x1400, v28
	ds_write2_b32 v15, v51, v52 offset0:40 offset1:106
	ds_write2_b32 v15, v53, v54 offset0:172 offset1:238
	v_add_u32_e32 v15, 0x1800, v28
	ds_write2_b32 v15, v55, v56 offset0:48 offset1:114
	ds_write2_b32 v15, v57, v58 offset0:180 offset1:246
	v_add_u32_e32 v15, 0x1c00, v28
	ds_write2_b32 v15, v59, v60 offset0:56 offset1:122
	ds_write2_b32 v15, v18, v14 offset0:188 offset1:254
	s_waitcnt lgkmcnt(0)
	ds_read2_b32 v[22:23], v30 offset0:33 offset1:41
	ds_read2_b32 v[24:25], v30 offset1:8
	ds_read2_b32 v[26:27], v30 offset0:66 offset1:74
	ds_read2_b32 v[40:41], v30 offset0:99 offset1:107
	ds_read2_b32 v[42:43], v30 offset0:132 offset1:140
	ds_read2_b32 v[44:45], v30 offset0:165 offset1:173
	ds_read2_b32 v[46:47], v30 offset0:198 offset1:206
	ds_read2_b32 v[48:49], v30 offset0:231 offset1:239
	v_lshlrev_b32_e32 v64, 1, v17
	v_or_b32_e32 v17, v16, v29
	v_lshl_add_u64 v[14:15], v[4:5], 0, v[64:65]
	v_lshlrev_b32_e32 v64, 11, v17
	v_or_b32_e32 v17, v16, v31
	s_waitcnt lgkmcnt(0)
	v_cvt_pk_bf16_f32 v18, v24, v22
	v_cvt_pk_bf16_f32 v19, v26, v40
	v_cvt_pk_bf16_f32 v20, v42, v44
	v_cvt_pk_bf16_f32 v21, v46, v48
	v_lshl_add_u64 v[50:51], v[14:15], 0, v[64:65]
	v_lshlrev_b32_e32 v64, 11, v17
	global_store_dwordx4 v[50:51], v[18:21], off sc1
	v_or_b32_e32 v17, v16, v32
	v_or_b32_e32 v16, v16, v33
	v_cvt_pk_bf16_f32 v18, v25, v23
	v_cvt_pk_bf16_f32 v19, v27, v41
	v_cvt_pk_bf16_f32 v20, v43, v45
	v_cvt_pk_bf16_f32 v21, v47, v49
	v_lshl_add_u64 v[22:23], v[14:15], 0, v[64:65]
	global_store_dwordx4 v[22:23], v[18:21], off sc1
	ds_read2_b32 v[22:23], v30 offset0:49 offset1:57
	ds_read2_b32 v[24:25], v30 offset0:16 offset1:24
	ds_read2_b32 v[26:27], v30 offset0:82 offset1:90
	ds_read2_b32 v[40:41], v30 offset0:115 offset1:123
	ds_read2_b32 v[42:43], v30 offset0:148 offset1:156
	ds_read2_b32 v[44:45], v30 offset0:181 offset1:189
	ds_read2_b32 v[46:47], v30 offset0:214 offset1:222
	ds_read2_b32 v[48:49], v30 offset0:247 offset1:255
	v_lshlrev_b32_e32 v64, 11, v17
	s_waitcnt lgkmcnt(6)
	v_cvt_pk_bf16_f32 v18, v24, v22
	s_waitcnt lgkmcnt(4)
	v_cvt_pk_bf16_f32 v19, v26, v40
	s_waitcnt lgkmcnt(2)
	v_cvt_pk_bf16_f32 v20, v42, v44
	s_waitcnt lgkmcnt(0)
	v_cvt_pk_bf16_f32 v21, v46, v48
	v_lshl_add_u64 v[50:51], v[14:15], 0, v[64:65]
	v_lshlrev_b32_e32 v64, 11, v16
	global_store_dwordx4 v[50:51], v[18:21], off sc1
	v_lshl_add_u64 v[14:15], v[14:15], 0, v[64:65]
	s_nop 0
	v_cvt_pk_bf16_f32 v18, v25, v23
	v_cvt_pk_bf16_f32 v19, v27, v41
	v_cvt_pk_bf16_f32 v20, v43, v45
	v_cvt_pk_bf16_f32 v21, v47, v49
	global_store_dwordx4 v[14:15], v[18:21], off sc1
	s_waitcnt lgkmcnt(0)

.LBB0_2253:
	s_andn2_saveexec_b64 s[6:7], s[6:7]
	s_cbranch_execz .LBB0_2255
	v_add_u32_e32 v15, 0x1400, v38
	v_and_b32_e32 v17, 0x1ffc0, v15
	v_and_b32_e32 v16, 0x3e0, v14
	v_or_b32_e32 v14, v17, v1
	v_lshlrev_b32_e32 v14, 10, v14
	v_or3_b32 v14, v14, v13, v16
	v_lshlrev_b32_e32 v64, 2, v14
	v_lshl_add_u64 v[14:15], s[12:13], 0, v[64:65]
	v_add_co_u32_e32 v18, vcc, 0x2000, v14
	s_mov_b32 s16, 0x10000
	s_nop 0
	v_addc_co_u32_e32 v19, vcc, 0, v15, vcc
	global_load_dword v21, v[18:19], off
	v_add_co_u32_e32 v18, vcc, 0x4000, v14
	global_load_dword v20, v64, s[12:13]
	s_nop 0
	v_addc_co_u32_e32 v19, vcc, 0, v15, vcc
	global_load_dword v22, v[18:19], off
	v_add_co_u32_e32 v18, vcc, 0x6000, v14
	s_nop 1
	v_addc_co_u32_e32 v19, vcc, 0, v15, vcc
	global_load_dword v23, v[18:19], off
	v_add_co_u32_e32 v18, vcc, 0x8000, v14
	s_nop 1
	v_addc_co_u32_e32 v19, vcc, 0, v15, vcc
	global_load_dword v24, v[18:19], off
	v_add_co_u32_e32 v18, vcc, 0xa000, v14
	s_nop 1
	v_addc_co_u32_e32 v19, vcc, 0, v15, vcc
	global_load_dword v25, v[18:19], off
	v_add_co_u32_e32 v18, vcc, 0xc000, v14
	s_nop 1
	v_addc_co_u32_e32 v19, vcc, 0, v15, vcc
	global_load_dword v26, v[18:19], off
	v_add_co_u32_e32 v18, vcc, 0xe000, v14
	s_nop 1
	v_addc_co_u32_e32 v19, vcc, 0, v15, vcc
	global_load_dword v27, v[18:19], off
	v_add_co_u32_e32 v18, vcc, s16, v14
	s_mov_b32 s16, 0x12000
	s_nop 0
	v_addc_co_u32_e32 v19, vcc, 0, v15, vcc
	global_load_dword v39, v[18:19], off
	v_add_co_u32_e32 v18, vcc, s16, v14
	s_mov_b32 s16, 0x14000
	s_nop 0
	v_addc_co_u32_e32 v19, vcc, 0, v15, vcc
	global_load_dword v40, v[18:19], off
	v_add_co_u32_e32 v18, vcc, s16, v14
	s_mov_b32 s16, 0x16000
	s_nop 0
	v_addc_co_u32_e32 v19, vcc, 0, v15, vcc
	global_load_dword v41, v[18:19], off
	v_add_co_u32_e32 v18, vcc, s16, v14
	s_mov_b32 s16, 0x18000
	s_nop 0
	v_addc_co_u32_e32 v19, vcc, 0, v15, vcc
	global_load_dword v42, v[18:19], off
	v_add_co_u32_e32 v18, vcc, s16, v14
	s_mov_b32 s16, 0x1a000
	s_nop 0
	v_addc_co_u32_e32 v19, vcc, 0, v15, vcc
	global_load_dword v43, v[18:19], off
	v_add_co_u32_e32 v18, vcc, s16, v14
	s_mov_b32 s16, 0x1c000
	s_nop 0
	v_addc_co_u32_e32 v19, vcc, 0, v15, vcc
	global_load_dword v44, v[18:19], off
	v_add_co_u32_e32 v18, vcc, s16, v14
	s_mov_b32 s16, 0x1e000
	s_nop 0
	v_addc_co_u32_e32 v19, vcc, 0, v15, vcc
	global_load_dword v45, v[18:19], off
	v_add_co_u32_e32 v18, vcc, s16, v14
	s_mov_b32 s16, 0x20000
	s_nop 0
	v_addc_co_u32_e32 v19, vcc, 0, v15, vcc
	global_load_dword v46, v[18:19], off
	v_add_co_u32_e32 v18, vcc, s16, v14
	s_mov_b32 s16, 0x22000
	s_nop 0
	v_addc_co_u32_e32 v19, vcc, 0, v15, vcc
	global_load_dword v47, v[18:19], off
	v_add_co_u32_e32 v18, vcc, s16, v14
	s_mov_b32 s16, 0x24000
	s_nop 0
	v_addc_co_u32_e32 v19, vcc, 0, v15, vcc
	global_load_dword v48, v[18:19], off
	v_add_co_u32_e32 v18, vcc, s16, v14
	s_mov_b32 s16, 0x26000
	s_nop 0
	v_addc_co_u32_e32 v19, vcc, 0, v15, vcc
	global_load_dword v49, v[18:19], off
	v_add_co_u32_e32 v18, vcc, s16, v14
	s_mov_b32 s16, 0x28000
	s_nop 0
	v_addc_co_u32_e32 v19, vcc, 0, v15, vcc
	global_load_dword v50, v[18:19], off
	v_add_co_u32_e32 v18, vcc, s16, v14
	s_mov_b32 s16, 0x2a000
	s_nop 0
	v_addc_co_u32_e32 v19, vcc, 0, v15, vcc
	global_load_dword v51, v[18:19], off
	v_add_co_u32_e32 v18, vcc, s16, v14
	s_mov_b32 s16, 0x2c000
	s_nop 0
	v_addc_co_u32_e32 v19, vcc, 0, v15, vcc
	global_load_dword v52, v[18:19], off
	v_add_co_u32_e32 v18, vcc, s16, v14
	s_mov_b32 s16, 0x2e000
	s_nop 0
	v_addc_co_u32_e32 v19, vcc, 0, v15, vcc
	global_load_dword v53, v[18:19], off
	v_add_co_u32_e32 v18, vcc, s16, v14
	s_mov_b32 s16, 0x30000
	s_nop 0
	v_addc_co_u32_e32 v19, vcc, 0, v15, vcc
	global_load_dword v54, v[18:19], off
	v_add_co_u32_e32 v18, vcc, s16, v14
	s_mov_b32 s16, 0x32000
	s_nop 0
	v_addc_co_u32_e32 v19, vcc, 0, v15, vcc
	global_load_dword v55, v[18:19], off
	v_add_co_u32_e32 v18, vcc, s16, v14
	s_mov_b32 s16, 0x34000
	s_nop 0
	v_addc_co_u32_e32 v19, vcc, 0, v15, vcc
	global_load_dword v56, v[18:19], off
	v_add_co_u32_e32 v18, vcc, s16, v14
	s_mov_b32 s16, 0x36000
	s_nop 0
	v_addc_co_u32_e32 v19, vcc, 0, v15, vcc
	global_load_dword v57, v[18:19], off
	v_add_co_u32_e32 v18, vcc, s16, v14
	s_mov_b32 s16, 0x38000
	s_nop 0
	v_addc_co_u32_e32 v19, vcc, 0, v15, vcc
	global_load_dword v58, v[18:19], off
	v_add_co_u32_e32 v18, vcc, s16, v14
	s_mov_b32 s16, 0x3a000
	s_nop 0
	v_addc_co_u32_e32 v19, vcc, 0, v15, vcc
	global_load_dword v59, v[18:19], off
	v_add_co_u32_e32 v18, vcc, s16, v14
	s_mov_b32 s16, 0x3c000
	s_nop 0
	v_addc_co_u32_e32 v19, vcc, 0, v15, vcc
	global_load_dword v60, v[18:19], off
	v_add_co_u32_e32 v18, vcc, s16, v14
	s_mov_b32 s16, 0x3e000
	s_nop 0
	v_addc_co_u32_e32 v19, vcc, 0, v15, vcc
	v_add_co_u32_e32 v14, vcc, s16, v14
	global_load_dword v18, v[18:19], off
	s_nop 0
	v_addc_co_u32_e32 v15, vcc, 0, v15, vcc
	global_load_dword v14, v[14:15], off
	v_add_u32_e32 v15, 0x400, v28
	s_waitcnt vmcnt(0)
	ds_write2_b32 v28, v20, v21 offset1:66
	ds_write2_b32 v28, v22, v23 offset0:132 offset1:198
	ds_write2_b32 v15, v24, v25 offset0:8 offset1:74
	ds_write2_b32 v15, v26, v27 offset0:140 offset1:206
	v_add_u32_e32 v15, 0x800, v28
	ds_write2_b32 v15, v39, v40 offset0:16 offset1:82
	ds_write2_b32 v15, v41, v42 offset0:148 offset1:214
	v_add_u32_e32 v15, 0xc00, v28
	ds_write2_b32 v15, v43, v44 offset0:24 offset1:90
	ds_write2_b32 v15, v45, v46 offset0:156 offset1:222
	v_add_u32_e32 v15, 0x1000, v28
	ds_write2_b32 v15, v47, v48 offset0:32 offset1:98
	ds_write2_b32 v15, v49, v50 offset0:164 offset1:230
	v_add_u32_e32 v15, 0x1400, v28
	ds_write2_b32 v15, v51, v52 offset0:40 offset1:106
	ds_write2_b32 v15, v53, v54 offset0:172 offset1:238
	v_add_u32_e32 v15, 0x1800, v28
	ds_write2_b32 v15, v55, v56 offset0:48 offset1:114
	ds_write2_b32 v15, v57, v58 offset0:180 offset1:246
	v_add_u32_e32 v15, 0x1c00, v28
	ds_write2_b32 v15, v59, v60 offset0:56 offset1:122
	ds_write2_b32 v15, v18, v14 offset0:188 offset1:254
	s_waitcnt lgkmcnt(0)
	ds_read2_b32 v[22:23], v30 offset0:33 offset1:41
	ds_read2_b32 v[24:25], v30 offset1:8
	ds_read2_b32 v[26:27], v30 offset0:66 offset1:74
	ds_read2_b32 v[40:41], v30 offset0:99 offset1:107
	ds_read2_b32 v[42:43], v30 offset0:132 offset1:140
	ds_read2_b32 v[44:45], v30 offset0:165 offset1:173
	ds_read2_b32 v[46:47], v30 offset0:198 offset1:206
	ds_read2_b32 v[48:49], v30 offset0:231 offset1:239
	v_lshlrev_b32_e32 v64, 1, v17
	v_or_b32_e32 v17, v16, v29
	v_lshl_add_u64 v[14:15], v[6:7], 0, v[64:65]
	v_lshlrev_b32_e32 v64, 11, v17
	v_or_b32_e32 v17, v16, v31
	s_waitcnt lgkmcnt(0)
	v_cvt_pk_bf16_f32 v18, v24, v22
	v_cvt_pk_bf16_f32 v19, v26, v40
	v_cvt_pk_bf16_f32 v20, v42, v44
	v_cvt_pk_bf16_f32 v21, v46, v48
	v_lshl_add_u64 v[50:51], v[14:15], 0, v[64:65]
	v_lshlrev_b32_e32 v64, 11, v17
	global_store_dwordx4 v[50:51], v[18:21], off sc1
	v_or_b32_e32 v17, v16, v32
	v_or_b32_e32 v16, v16, v33
	v_cvt_pk_bf16_f32 v18, v25, v23
	v_cvt_pk_bf16_f32 v19, v27, v41
	v_cvt_pk_bf16_f32 v20, v43, v45
	v_cvt_pk_bf16_f32 v21, v47, v49
	v_lshl_add_u64 v[22:23], v[14:15], 0, v[64:65]
	global_store_dwordx4 v[22:23], v[18:21], off sc1
	ds_read2_b32 v[22:23], v30 offset0:49 offset1:57
	ds_read2_b32 v[24:25], v30 offset0:16 offset1:24
	ds_read2_b32 v[26:27], v30 offset0:82 offset1:90
	ds_read2_b32 v[40:41], v30 offset0:115 offset1:123
	ds_read2_b32 v[42:43], v30 offset0:148 offset1:156
	ds_read2_b32 v[44:45], v30 offset0:181 offset1:189
	ds_read2_b32 v[46:47], v30 offset0:214 offset1:222
	ds_read2_b32 v[48:49], v30 offset0:247 offset1:255
	v_lshlrev_b32_e32 v64, 11, v17
	s_waitcnt lgkmcnt(6)
	v_cvt_pk_bf16_f32 v18, v24, v22
	s_waitcnt lgkmcnt(4)
	v_cvt_pk_bf16_f32 v19, v26, v40
	s_waitcnt lgkmcnt(2)
	v_cvt_pk_bf16_f32 v20, v42, v44
	s_waitcnt lgkmcnt(0)
	v_cvt_pk_bf16_f32 v21, v46, v48
	v_lshl_add_u64 v[50:51], v[14:15], 0, v[64:65]
	v_lshlrev_b32_e32 v64, 11, v16
	global_store_dwordx4 v[50:51], v[18:21], off sc1
	v_lshl_add_u64 v[14:15], v[14:15], 0, v[64:65]
	s_nop 0
	v_cvt_pk_bf16_f32 v18, v25, v23
	v_cvt_pk_bf16_f32 v19, v27, v41
	v_cvt_pk_bf16_f32 v20, v43, v45
	v_cvt_pk_bf16_f32 v21, v47, v49
	global_store_dwordx4 v[14:15], v[18:21], off sc1
	s_waitcnt lgkmcnt(0)

.LBB0_2256:
	s_andn2_saveexec_b64 s[16:17], s[4:5]
	s_cbranch_execz .LBB0_2245
	s_mov_b32 s4, 0x2e8ba2e9
	v_mul_hi_i32 v14, v0, s4
	v_lshrrev_b32_e32 v15, 31, v14
	v_ashrrev_i32_e32 v14, 4, v14
	v_add_u32_e32 v15, v14, v15
	s_movk_i32 s4, 0xffa8
	v_mad_u64_u32 v[20:21], s[4:5], v15, s4, v[0:1]
	s_movk_i32 s4, 0xf500
	s_nop 0
	v_mad_u64_u32 v[18:19], s[4:5], v15, s4, v[12:13]
	v_add_u32_e32 v16, 0x600, v18
	v_lshlrev_b32_e32 v14, 6, v15
	v_ashrrev_i32_e32 v17, 31, v16
	v_or_b32_e32 v15, v14, v1
	v_lshl_add_u64 v[22:23], v[16:17], 2, v[10:11]
	v_mad_i64_i32 v[24:25], s[4:5], v15, s78, v[22:23]
	v_or_b32_e32 v19, 2, v15
	global_load_dword v17, v[24:25], off
	v_mad_i64_i32 v[24:25], s[4:5], v19, s78, v[22:23]
	v_or_b32_e32 v21, 4, v15
	global_load_dword v19, v[24:25], off
	v_mad_i64_i32 v[24:25], s[4:5], v21, s78, v[22:23]
	global_load_dword v21, v[24:25], off
	v_or_b32_e32 v24, 6, v15
	v_mad_i64_i32 v[24:25], s[4:5], v24, s78, v[22:23]
	global_load_dword v26, v[24:25], off
	v_or_b32_e32 v24, 8, v15
	v_mad_i64_i32 v[24:25], s[4:5], v24, s78, v[22:23]
	global_load_dword v27, v[24:25], off
	v_or_b32_e32 v24, 10, v15
	v_mad_i64_i32 v[24:25], s[4:5], v24, s78, v[22:23]
	global_load_dword v39, v[24:25], off
	v_or_b32_e32 v24, 12, v15
	v_mad_i64_i32 v[24:25], s[4:5], v24, s78, v[22:23]
	global_load_dword v40, v[24:25], off
	v_or_b32_e32 v24, 14, v15
	v_mad_i64_i32 v[24:25], s[4:5], v24, s78, v[22:23]
	global_load_dword v41, v[24:25], off
	v_or_b32_e32 v24, 16, v15
	v_mad_i64_i32 v[24:25], s[4:5], v24, s78, v[22:23]
	global_load_dword v42, v[24:25], off
	v_or_b32_e32 v24, 18, v15
	v_mad_i64_i32 v[24:25], s[4:5], v24, s78, v[22:23]
	global_load_dword v43, v[24:25], off
	v_or_b32_e32 v24, 20, v15
	v_mad_i64_i32 v[24:25], s[4:5], v24, s78, v[22:23]
	global_load_dword v44, v[24:25], off
	v_or_b32_e32 v24, 22, v15
	v_mad_i64_i32 v[24:25], s[4:5], v24, s78, v[22:23]
	global_load_dword v45, v[24:25], off
	v_or_b32_e32 v24, 24, v15
	v_mad_i64_i32 v[24:25], s[4:5], v24, s78, v[22:23]
	global_load_dword v46, v[24:25], off
	v_or_b32_e32 v24, 26, v15
	v_mad_i64_i32 v[24:25], s[4:5], v24, s78, v[22:23]
	global_load_dword v47, v[24:25], off
	v_or_b32_e32 v24, 28, v15
	v_mad_i64_i32 v[24:25], s[4:5], v24, s78, v[22:23]
	global_load_dword v48, v[24:25], off
	v_or_b32_e32 v24, 30, v15
	v_mad_i64_i32 v[24:25], s[4:5], v24, s78, v[22:23]
	global_load_dword v49, v[24:25], off
	v_or_b32_e32 v24, 32, v15
	v_mad_i64_i32 v[24:25], s[4:5], v24, s78, v[22:23]
	global_load_dword v50, v[24:25], off
	v_or_b32_e32 v24, 34, v15
	v_mad_i64_i32 v[24:25], s[4:5], v24, s78, v[22:23]
	global_load_dword v51, v[24:25], off
	v_or_b32_e32 v24, 36, v15
	v_mad_i64_i32 v[24:25], s[4:5], v24, s78, v[22:23]
	global_load_dword v52, v[24:25], off
	v_or_b32_e32 v24, 38, v15
	v_mad_i64_i32 v[24:25], s[4:5], v24, s78, v[22:23]
	global_load_dword v53, v[24:25], off
	v_or_b32_e32 v24, 40, v15
	v_mad_i64_i32 v[24:25], s[4:5], v24, s78, v[22:23]
	global_load_dword v54, v[24:25], off
	v_or_b32_e32 v24, 42, v15
	v_mad_i64_i32 v[24:25], s[4:5], v24, s78, v[22:23]
	global_load_dword v55, v[24:25], off
	v_or_b32_e32 v24, 44, v15
	v_mad_i64_i32 v[24:25], s[4:5], v24, s78, v[22:23]
	global_load_dword v56, v[24:25], off
	v_or_b32_e32 v24, 46, v15
	v_mad_i64_i32 v[24:25], s[4:5], v24, s78, v[22:23]
	global_load_dword v57, v[24:25], off
	v_or_b32_e32 v24, 48, v15
	v_mad_i64_i32 v[24:25], s[4:5], v24, s78, v[22:23]
	global_load_dword v58, v[24:25], off
	v_or_b32_e32 v24, 50, v15
	v_mad_i64_i32 v[24:25], s[4:5], v24, s78, v[22:23]
	global_load_dword v59, v[24:25], off
	v_or_b32_e32 v24, 52, v15
	v_mad_i64_i32 v[24:25], s[4:5], v24, s78, v[22:23]
	global_load_dword v60, v[24:25], off
	v_or_b32_e32 v24, 54, v15
	v_mad_i64_i32 v[24:25], s[4:5], v24, s78, v[22:23]
	global_load_dword v61, v[24:25], off
	v_or_b32_e32 v24, 56, v15
	v_mad_i64_i32 v[24:25], s[4:5], v24, s78, v[22:23]
	global_load_dword v62, v[24:25], off
	v_or_b32_e32 v24, 58, v15
	v_mad_i64_i32 v[24:25], s[4:5], v24, s78, v[22:23]
	global_load_dword v63, v[24:25], off
	v_or_b32_e32 v24, 60, v15
	v_or_b32_e32 v15, 62, v15
	v_mad_i64_i32 v[24:25], s[4:5], v24, s78, v[22:23]
	v_mad_i64_i32 v[22:23], s[4:5], v15, s78, v[22:23]
	global_load_dword v24, v[24:25], off
	s_movk_i32 s4, 0x17f
	global_load_dword v15, v[22:23], off
	s_waitcnt vmcnt(0)
	ds_write2_b32 v28, v17, v19 offset1:66
	ds_write2_b32 v28, v21, v26 offset0:132 offset1:198
	v_add_u32_e32 v17, 0x400, v28
	ds_write2_b32 v17, v27, v39 offset0:8 offset1:74
	ds_write2_b32 v17, v40, v41 offset0:140 offset1:206
	v_add_u32_e32 v17, 0x800, v28
	ds_write2_b32 v17, v42, v43 offset0:16 offset1:82
	ds_write2_b32 v17, v44, v45 offset0:148 offset1:214
	v_add_u32_e32 v17, 0xc00, v28
	ds_write2_b32 v17, v46, v47 offset0:24 offset1:90
	ds_write2_b32 v17, v48, v49 offset0:156 offset1:222
	v_add_u32_e32 v17, 0x1000, v28
	ds_write2_b32 v17, v50, v51 offset0:32 offset1:98
	ds_write2_b32 v17, v52, v53 offset0:164 offset1:230
	v_add_u32_e32 v17, 0x1400, v28
	ds_write2_b32 v17, v54, v55 offset0:40 offset1:106
	ds_write2_b32 v17, v56, v57 offset0:172 offset1:238
	v_add_u32_e32 v17, 0x1800, v28
	ds_write2_b32 v17, v58, v59 offset0:48 offset1:114
	ds_write2_b32 v17, v60, v61 offset0:180 offset1:246
	v_add_u32_e32 v17, 0x1c00, v28
	ds_write2_b32 v17, v62, v63 offset0:56 offset1:122
	ds_write2_b32 v17, v24, v15 offset0:188 offset1:254
	s_waitcnt lgkmcnt(0)
	v_and_b32_e32 v15, 0x7fffff0, v20
	ds_read2_b32 v[20:21], v30 offset1:33
	ds_read2_b32 v[22:23], v30 offset0:66 offset1:99
	ds_read2_b32 v[24:25], v30 offset0:132 offset1:165
	ds_read2_b32 v[26:27], v30 offset0:198 offset1:231
	v_add_u32_e32 v41, v18, v29
	v_cmp_eq_u32_e32 vcc, 64, v15
	v_and_b32_e32 v39, 0x9e0, v16
	v_add_u32_e32 v15, 0x600, v41
	v_cmp_lt_u32_e64 s[4:5], s4, v18
	s_and_saveexec_b64 s[6:7], s[4:5]
	s_xor_b64 s[6:7], exec, s[6:7]
	v_or_b32_e32 v17, v39, v34
	v_cndmask_b32_e32 v18, v15, v17, vcc
	s_or_saveexec_b64 s[18:19], s[6:7]
	v_and_b32_e32 v40, 0x7c0, v16
	s_xor_b64 exec, exec, s[18:19]
	v_and_b32_e32 v15, 39, v15
	v_lshlrev_b32_e32 v16, 1, v15
	v_subrev_u32_e32 v17, 63, v16
	v_cmp_gt_u32_e64 s[6:7], 32, v15
	s_nop 1
	v_cndmask_b32_e64 v15, v17, v16, s[6:7]
	v_add_u32_e32 v18, v15, v40
	s_or_b64 exec, exec, s[18:19]
	v_ashrrev_i32_e32 v15, 31, v14
	v_ashrrev_i32_e32 v19, 31, v18
	v_lshl_add_u64 v[14:15], v[14:15], 1, v[8:9]
	v_lshlrev_b64 v[16:17], 11, v[18:19]
	s_waitcnt lgkmcnt(0)
	v_cvt_pk_bf16_f32 v20, v20, v21
	v_cvt_pk_bf16_f32 v21, v22, v23
	v_cvt_pk_bf16_f32 v22, v24, v25
	v_cvt_pk_bf16_f32 v23, v26, v27
	v_lshl_add_u64 v[16:17], v[14:15], 0, v[16:17]
	global_store_dwordx4 v[16:17], v[20:23], off sc1
	ds_read2_b32 v[16:17], v30 offset0:8 offset1:41
	ds_read2_b32 v[18:19], v30 offset0:74 offset1:107
	ds_read2_b32 v[20:21], v30 offset0:140 offset1:173
	ds_read2_b32 v[22:23], v30 offset0:206 offset1:239
	v_add_u32_e32 v25, 0x608, v41
	s_and_saveexec_b64 s[6:7], s[4:5]
	s_xor_b64 s[6:7], exec, s[6:7]
	v_or_b32_e32 v24, v39, v35
	v_cndmask_b32_e32 v24, v25, v24, vcc
	s_andn2_saveexec_b64 s[18:19], s[6:7]
	v_and_b32_e32 v24, 47, v25
	v_lshlrev_b32_e32 v25, 1, v24
	v_subrev_u32_e32 v26, 63, v25
	v_cmp_gt_u32_e64 s[6:7], 32, v24
	s_nop 1
	v_cndmask_b32_e64 v24, v26, v25, s[6:7]
	v_add_u32_e32 v24, v24, v40
	s_or_b64 exec, exec, s[18:19]
	v_ashrrev_i32_e32 v25, 31, v24
	s_waitcnt lgkmcnt(3)
	v_cvt_pk_bf16_f32 v16, v16, v17
	s_waitcnt lgkmcnt(2)
	v_cvt_pk_bf16_f32 v17, v18, v19
	s_waitcnt lgkmcnt(1)
	v_cvt_pk_bf16_f32 v18, v20, v21
	v_lshlrev_b64 v[20:21], 11, v[24:25]
	s_waitcnt lgkmcnt(0)
	v_cvt_pk_bf16_f32 v19, v22, v23
	v_lshl_add_u64 v[20:21], v[14:15], 0, v[20:21]
	global_store_dwordx4 v[20:21], v[16:19], off sc1
	ds_read2_b32 v[16:17], v30 offset0:16 offset1:49
	ds_read2_b32 v[18:19], v30 offset0:82 offset1:115
	ds_read2_b32 v[20:21], v30 offset0:148 offset1:181
	ds_read2_b32 v[22:23], v30 offset0:214 offset1:247
	v_add_u32_e32 v25, 0x610, v41
	s_and_saveexec_b64 s[6:7], s[4:5]
	s_xor_b64 s[6:7], exec, s[6:7]
	v_or_b32_e32 v24, v39, v36
	v_cndmask_b32_e32 v24, v25, v24, vcc
	s_andn2_saveexec_b64 s[18:19], s[6:7]
	v_and_b32_e32 v24, 55, v25
	v_lshlrev_b32_e32 v25, 1, v24
	v_subrev_u32_e32 v26, 63, v25
	v_cmp_gt_u32_e64 s[6:7], 32, v24
	s_nop 1
	v_cndmask_b32_e64 v24, v26, v25, s[6:7]
	v_add_u32_e32 v24, v24, v40
	s_or_b64 exec, exec, s[18:19]
	v_ashrrev_i32_e32 v25, 31, v24
	s_waitcnt lgkmcnt(3)
	v_cvt_pk_bf16_f32 v16, v16, v17
	s_waitcnt lgkmcnt(2)
	v_cvt_pk_bf16_f32 v17, v18, v19
	s_waitcnt lgkmcnt(1)
	v_cvt_pk_bf16_f32 v18, v20, v21
	v_lshlrev_b64 v[20:21], 11, v[24:25]
	s_waitcnt lgkmcnt(0)
	v_cvt_pk_bf16_f32 v19, v22, v23
	v_lshl_add_u64 v[20:21], v[14:15], 0, v[20:21]
	global_store_dwordx4 v[20:21], v[16:19], off sc1
	ds_read2_b32 v[16:17], v30 offset0:24 offset1:57
	ds_read2_b32 v[18:19], v30 offset0:90 offset1:123
	ds_read2_b32 v[20:21], v30 offset0:156 offset1:189
	ds_read2_b32 v[22:23], v30 offset0:222 offset1:255
	v_add_u32_e32 v25, 0x618, v41
	s_and_saveexec_b64 s[6:7], s[4:5]
	s_xor_b64 s[4:5], exec, s[6:7]
	v_or_b32_e32 v24, v39, v37
	v_cndmask_b32_e32 v24, v25, v24, vcc
	s_andn2_saveexec_b64 s[4:5], s[4:5]
	s_cbranch_execz .LBB0_2244
	v_and_b32_e32 v24, 63, v25
	v_lshlrev_b32_e32 v25, 1, v24
	v_subrev_u32_e32 v26, 63, v25
	v_cmp_gt_u32_e32 vcc, 32, v24
	s_nop 1
	v_cndmask_b32_e32 v24, v26, v25, vcc
	v_add_u32_e32 v24, v24, v40
	s_branch .LBB0_2244

.LBB0_2275:
	s_cmp_lt_u32 s74, 3
	s_cbranch_scc0 .Lmy_e_skip
	v_readlane_b32 s8, v254, 10
	v_readlane_b32 s9, v254, 11
	v_mov_b32_e32 v0, 0x3880
	s_cmpk_lt_i32 s2, 0xc0
	s_cbranch_scc1 .Lmy_e_nopub
	v_mov_b32_e32 v1, 1
	s_nop 1
	global_atomic_add v0, v1, s[8:9]
.Lmy_e_nopub:
	v_readlane_b32 s4, v255, 46
	s_cmp_lg_u32 s4, 0
	s_cbranch_scc0 .Lmy_e_skip
	s_add_i32 s4, s74, 1
	s_lshl_b32 s4, s4, 7
	s_mov_b32 s5, 0
.Lmy_e_poll:
	global_load_dword v1, v0, s[8:9] sc1
	s_waitcnt vmcnt(0)
	v_cmp_gt_u32_e32 vcc, s4, v1
	s_cbranch_vccz .Lmy_e_skip
	s_sleep 2
	s_add_i32 s5, s5, 1
	s_cmp_lt_u32 s5, 0x100000
	s_cbranch_scc1 .Lmy_e_poll
.Lmy_e_skip:
	v_readlane_b32 s7, v255, 17
	s_waitcnt vmcnt(0) expcnt(0) lgkmcnt(0)
	s_mov_b64 s[4:5], exec
	v_mov_b32_e32 v0, s7
	v_readlane_b32 s7, v255, 18
	ds_read_b32 v2, v0
	v_mbcnt_lo_u32_b32 v1, s4, 0
	v_mov_b32_e32 v0, s7
	ds_read_b32 v0, v0
	v_mbcnt_hi_u32_b32 v1, s5, v1
	s_lshl_b32 s20, s6, 6
	v_cmp_eq_u32_e32 vcc, 0, v1
	s_and_saveexec_b64 s[6:7], vcc
	s_cbranch_execz .LBB0_2277
	s_add_i32 s96, s20, 0x500
	s_lshr_b32 s9, s20, 1
	s_add_i32 s9, s9, 0xe50
	v_readlane_b32 s8, v255, 46
	s_cmp_lg_u32 s74, 3
	s_cselect_b32 s8, s8, 0
	s_cmp_lg_u32 s8, 0
	s_cselect_b32 s96, s9, s96
	s_lshl_b64 s[8:9], s[96:97], 2
	v_readlane_b32 s10, v254, 10
	v_readlane_b32 s11, v254, 11
	s_add_u32 s8, s10, s8
	s_addc_u32 s9, s11, s9
	s_bcnt1_i32_b64 s4, s[4:5]
	v_mov_b32_e32 v3, s4
	global_atomic_add v3, v65, v3, s[8:9] sc0
.LBB0_2277:
	s_or_b64 exec, exec, s[6:7]
	s_waitcnt lgkmcnt(1)
	v_cvt_f32_u32_e32 v4, v2
	s_waitcnt vmcnt(0)
	v_readfirstlane_b32 s4, v3
	buffer_inv sc1
	v_sub_u32_e32 v3, 0, v2
	v_rcp_iflag_f32_e32 v4, v4
	v_add_u32_e32 v5, s4, v1
	v_mul_f32_e32 v4, 0x4f7ffffe, v4
	v_cvt_u32_f32_e32 v4, v4
	v_mul_lo_u32 v1, v3, v4
	v_mul_hi_u32 v1, v4, v1
	v_add_u32_e32 v1, v4, v1
	v_mul_hi_u32 v1, v5, v1
	v_mul_lo_u32 v3, v1, v2
	v_sub_u32_e32 v3, v5, v3
	v_add_u32_e32 v4, 1, v1
	v_cmp_ge_u32_e32 vcc, v3, v2
	s_nop 1
	v_cndmask_b32_e32 v1, v1, v4, vcc
	v_sub_u32_e32 v4, v3, v2
	v_cndmask_b32_e32 v3, v3, v4, vcc
	v_add_u32_e32 v4, 1, v1
	v_cmp_ge_u32_e32 vcc, v3, v2
	v_add_u32_e32 v3, 1, v5
	s_nop 0
	v_cndmask_b32_e32 v1, v1, v4, vcc
	v_mul_lo_u32 v4, v2, v1
	v_add_u32_e32 v2, v4, v2
	v_cmp_ne_u32_e32 vcc, v3, v2
	s_and_saveexec_b64 s[4:5], vcc
	s_xor_b64 s[4:5], exec, s[4:5]
	s_cbranch_execz .LBB0_2291
	v_readlane_b32 s6, v255, 46
	s_cmp_lg_u32 s74, 3
	s_cselect_b32 s6, s6, 0
	s_cmp_lg_u32 s6, 0
	s_cbranch_scc0 .Lmy_gpoll_e
	s_lshr_b32 s96, s20, 1
	s_add_i32 s96, s96, 0xe50
	s_lshl_b64 s[6:7], s[96:97], 2
	v_readlane_b32 s8, v254, 10
	v_readlane_b32 s9, v254, 11
	s_add_u32 s8, s8, s6
	s_addc_u32 s9, s9, s7
	s_mov_b32 s21, 0
	s_waitcnt lgkmcnt(0)
	s_nop 1

.Lmy_exit_e:
	s_getpc_b64 s[98:99]

.LBB0_2292:
	v_readlane_b32 s4, v255, 46
	s_cmp_lg_u32 s74, 3
	s_cselect_b32 s4, s4, 0
	s_cmp_lg_u32 s4, 0
	s_cbranch_scc0 .Lmy_gl_e
	s_waitcnt vmcnt(0)
	s_branch .Lmy_exit_e
